# prepper: wait+staging copies moved ahead of the cumulative-sum store so its ack is not waited for; otherwise v29
# speedup vs baseline: 1.0093x; 1.0093x over previous
.Lpp_chunk:
	s_add_i32 s75, s74, 1
	s_cmp_ge_u32 s75, s31
	s_cbranch_scc1 .Lpp_cs
	s_waitcnt vmcnt(0)
	v_mov_b32_e32 v36, v200
	v_mov_b32_e32 v37, v201
	v_mov_b32_e32 v38, v202
	v_mov_b32_e32 v39, v203
	v_mov_b32_e32 v40, v204
	v_mov_b32_e32 v41, v205
	v_mov_b32_e32 v42, v206
	v_mov_b32_e32 v43, v207
	v_mov_b32_e32 v86, v208
	v_mov_b32_e32 v87, v209
	v_mov_b32_e32 v88, v210
	v_mov_b32_e32 v89, v211
	v_mov_b32_e32 v90, v212
	v_mov_b32_e32 v91, v213
	v_mov_b32_e32 v92, v214
	v_mov_b32_e32 v93, v215
	v_mov_b32_e32 v94, v216
	v_mov_b32_e32 v95, v217
	v_mov_b32_e32 v50, v218
	v_mov_b32_e32 v51, v219
	v_mov_b32_e32 v96, v220
	v_mov_b32_e32 v97, v221
	v_mov_b32_e32 v48, v222
.Lpp_cs:
	s_and_saveexec_b64 s[16:17], s[4:5]
	s_cbranch_execz .Lpp_cs_done
	v_lshl_add_u32 v110, s33, 9, v134
	ds_read_b128 v[112:115], v110 offset:49920
	v_add_u32_e32 v110, s73, v69
	v_add_u32_e32 v116, s27, v146
	v_cndmask_b32_e64 v110, v116, v110, s[40:41]
	s_waitcnt lgkmcnt(0)
	v_mov_b32_e32 v116, v113
	v_mov_b32_e32 v117, v114
	v_mov_b32_e32 v113, v115
	v_pk_add_f32 v[112:113], v[116:117], v[112:113]
	s_nop 0
	v_add_f32_e32 v114, v112, v113
	v_add_u32_e32 v112, s26, v110
	v_ashrrev_i32_e32 v113, 31, v112
	v_lshlrev_b64 v[112:113], 7, v[112:113]
	v_lshl_add_u64 v[112:113], s[42:43], 0, v[112:113]
	global_store_dword v[112:113], v114, off
.Lpp_cs_done:
	s_or_b64 exec, exec, s[16:17]
	s_xor_b32 s33, s33, 1
	s_cmp_ge_u32 s75, s31
	s_cbranch_scc1 .Lpp_nomore
	s_add_i32 s16, s74, 2
	s_cmp_ge_u32 s16, s31
	s_cbranch_scc1 .Lpp_nopf
	v_lshl_or_b32 v110, s16, 4, v68
	v_xad_u32 v111, v110, -1, s46
	v_cndmask_b32_e64 v110, v111, v110, s[40:41]
	v_add_u32_e32 v112, s26, v110
	v_mov_b64_e32 v[110:111], s[2:3]
	v_mad_i64_i32 v[110:111], s[16:17], v112, s63, v[110:111]
	v_lshl_add_u64 v[114:115], v[84:85], 1, v[110:111]
	v_lshl_add_u64 v[116:117], v[110:111], 0, s[6:7]
	v_lshl_add_u64 v[110:111], v[110:111], 0, s[28:29]
	v_lshl_add_u64 v[118:119], v[74:75], 1, v[110:111]
	v_lshl_add_u64 v[120:121], v[118:119], 0, s[36:37]
	v_lshl_add_u64 v[122:123], v[118:119], 0, s[66:67]
	v_lshl_add_u64 v[124:125], v[114:115], 0, s[92:93]
	v_lshl_add_u64 v[126:127], v[116:117], 0, s[92:93]
	v_lshl_add_u64 v[128:129], v[118:119], 0, s[92:93]
	global_load_dwordx2 v[216:217], v[114:115], off
	global_load_dwordx2 v[218:219], v[114:115], off offset:2048
	global_load_dwordx2 v[220:221], v[124:125], off
	global_load_dword v222, v[126:127], off offset:2816
	global_load_dwordx4 v[200:203], v[128:129], off offset:2048
	global_load_dwordx4 v[208:211], v[128:129], off offset:2304
	global_load_dwordx4 v[204:207], v[120:121], off offset:64
	global_load_dwordx4 v[212:215], v[122:123], off offset:64
